# GEMM fragment reads as conflict-free ds_read_b64 pairs (odd k-chunk lanes take their halves in swapped order in both operands)
# speedup vs baseline: 1.0129x; 1.0037x over previous
.LBB0_203:
	s_cmp_lt_i32 s24, 0
	s_cbranch_scc1 .LBB0_219
	s_lshr_b32 s4, s24, 3
	s_mul_hi_u32 s4, s4, 0x97b425f
	s_mul_i32 s5, s4, 0xd8
	s_sub_i32 s8, s24, s5
	s_lshl_b32 s5, s37, 4
	s_lshl_b32 s4, s4, 3
	s_add_i32 s4, s4, s5
	s_and_b32 s5, s8, 7
	s_or_b32 s4, s4, s5
	s_lshl_b32 s48, s4, 7
	s_lshl_b32 s4, s8, 4
	v_or_b32_e32 v100, s48, v214
	s_and_b32 s6, s4, 0xf80
	v_readfirstlane_b32 s4, v104
	s_and_b32 s49, s4, 64
	s_lshr_b32 s7, s4, 1
	s_and_b32 s50, s7, 0x7fffffc0
	s_lshr_b32 s7, s4, 6
	s_lshl_b32 s7, s7, 10
	v_bfe_u32 v217, v108, 1, 3
	v_lshlrev_b32_e32 v217, 4, v217
	v_xor_b32_e32 v217, v217, v110
	v_or_b32_e32 v218, s50, v108
	v_lshl_add_u32 v144, v218, 7, v217
	v_xor_b32_e32 v218, 64, v144
	v_or_b32_e32 v219, s49, v108
	v_lshl_add_u32 v100, v219, 7, v217
	v_xor_b32_e32 v219, 64, v100
	v_bfe_u32 v64, v214, 1, 3
	v_xor_b32_e32 v64, v64, v102
	v_lshlrev_b32_e32 v64, 4, v64
	v_lshl_add_u32 v64, v214, 11, v64
	v_add_u32_e32 v65, 0x10000, v64
	v_add_u32_e32 v66, 0x20000, v64
	v_add_u32_e32 v67, 0x30000, v64
	s_lshl_b32 s12, s48, 11
	s_add_u32 s4, s90, s12
	s_addc_u32 s5, s91, 0
	s_lshl_b32 s12, s6, 11
	s_add_u32 s24, s92, s12
	s_addc_u32 s25, s93, 0
	s_add_u32 m0, s7, 0x0
	s_nop 0
	global_load_lds_dwordx4 v64, s[4:5]
	s_add_u32 m0, s7, 0x1000
	s_nop 0
	global_load_lds_dwordx4 v65, s[4:5]
	s_add_u32 m0, s7, 0x2000
	s_nop 0
	global_load_lds_dwordx4 v66, s[4:5]
	s_add_u32 m0, s7, 0x3000
	s_nop 0
	global_load_lds_dwordx4 v67, s[4:5]
	s_add_u32 m0, s7, 0x9000
	s_nop 0
	global_load_lds_dwordx4 v64, s[24:25]
	s_add_u32 m0, s7, 0xa000
	s_nop 0
	global_load_lds_dwordx4 v65, s[24:25]
	s_add_u32 m0, s7, 0xb000
	s_nop 0
	global_load_lds_dwordx4 v66, s[24:25]
	s_add_u32 m0, s7, 0xc000
	s_nop 0
	global_load_lds_dwordx4 v67, s[24:25]
	s_add_u32 s4, s4, 0x80
	s_addc_u32 s5, s5, 0
	s_add_u32 s24, s24, 0x80
	s_addc_u32 s25, s25, 0
	v_mov_b64_e32 v[0:1], 0
	v_mov_b64_e32 v[2:3], 0
	v_mov_b64_e32 v[4:5], 0
	v_mov_b64_e32 v[6:7], 0
	v_mov_b64_e32 v[8:9], 0
	v_mov_b64_e32 v[10:11], 0
	v_mov_b64_e32 v[12:13], 0
	v_mov_b64_e32 v[14:15], 0
	v_mov_b64_e32 v[16:17], 0
	v_mov_b64_e32 v[18:19], 0
	v_mov_b64_e32 v[20:21], 0
	v_mov_b64_e32 v[22:23], 0
	v_mov_b64_e32 v[24:25], 0
	v_mov_b64_e32 v[26:27], 0
	v_mov_b64_e32 v[28:29], 0
	v_mov_b64_e32 v[30:31], 0
	v_mov_b64_e32 v[32:33], 0
	v_mov_b64_e32 v[34:35], 0
	v_mov_b64_e32 v[36:37], 0
	v_mov_b64_e32 v[38:39], 0
	v_mov_b64_e32 v[40:41], 0
	v_mov_b64_e32 v[42:43], 0
	v_mov_b64_e32 v[44:45], 0
	v_mov_b64_e32 v[46:47], 0
	v_mov_b64_e32 v[48:49], 0
	v_mov_b64_e32 v[50:51], 0
	v_mov_b64_e32 v[52:53], 0
	v_mov_b64_e32 v[54:55], 0
	v_mov_b64_e32 v[56:57], 0
	v_mov_b64_e32 v[58:59], 0
	v_mov_b64_e32 v[60:61], 0
	v_mov_b64_e32 v[62:63], 0
	s_mov_b32 s9, 0
	s_waitcnt vmcnt(0)
	s_barrier
	v_bfe_u32 v251, v104, 4, 1
	v_lshlrev_b32_e32 v251, 3, v251
	v_add_u32_e32 v220, v144, v251
	v_sub_u32_e32 v221, v144, v251
	v_add_u32_e32 v221, 8, v221
	v_add_u32_e32 v222, v218, v251
	v_sub_u32_e32 v223, v218, v251
	v_add_u32_e32 v223, 8, v223
	v_add_u32_e32 v224, v100, v251
	v_sub_u32_e32 v225, v100, v251
	v_add_u32_e32 v225, 8, v225
	v_add_u32_e32 v226, v219, v251
	v_sub_u32_e32 v227, v219, v251
	v_add_u32_e32 v227, 8, v227
	s_setprio 2
.Lg1_loop:
	s_add_u32 m0, s7, 0x4800
	s_nop 0
	global_load_lds_dwordx4 v64, s[4:5]
	s_add_u32 m0, s7, 0x5800
	s_nop 0
	global_load_lds_dwordx4 v65, s[4:5]
	s_add_u32 m0, s7, 0x6800
	s_nop 0
	global_load_lds_dwordx4 v66, s[4:5]
	s_add_u32 m0, s7, 0x7800
	s_nop 0
	global_load_lds_dwordx4 v67, s[4:5]
	s_add_u32 m0, s7, 0xd800
	s_nop 0
	global_load_lds_dwordx4 v64, s[24:25]
	s_add_u32 m0, s7, 0xe800
	s_nop 0
	global_load_lds_dwordx4 v65, s[24:25]
	s_add_u32 m0, s7, 0xf800
	s_nop 0
	global_load_lds_dwordx4 v66, s[24:25]
	s_add_u32 m0, s7, 0x10800
	s_nop 0
	global_load_lds_dwordx4 v67, s[24:25]
	s_add_u32 s4, s4, 0x80
	s_addc_u32 s5, s5, 0
	s_add_u32 s24, s24, 0x80
	s_addc_u32 s25, s25, 0
	ds_read_b64 v[68:69], v220 offset:0
	ds_read_b64 v[70:71], v221 offset:0
	ds_read_b64 v[84:85], v224 offset:36864
	ds_read_b64 v[86:87], v225 offset:36864
	ds_read_b64 v[88:89], v224 offset:38912
	ds_read_b64 v[90:91], v225 offset:38912
	ds_read_b64 v[92:93], v224 offset:40960
	ds_read_b64 v[94:95], v225 offset:40960
	ds_read_b64 v[158:159], v224 offset:43008
	ds_read_b64 v[160:161], v225 offset:43008
	ds_read_b64 v[72:73], v220 offset:2048
	ds_read_b64 v[74:75], v221 offset:2048
	ds_read_b64 v[76:77], v220 offset:4096
	ds_read_b64 v[78:79], v221 offset:4096
	s_waitcnt lgkmcnt(12)
	s_waitcnt lgkmcnt(10)
	v_mfma_f32_16x16x32_bf16 v[44:47], v[68:71], v[84:87], v[44:47]
	ds_read_b64 v[80:81], v220 offset:6144
	ds_read_b64 v[82:83], v221 offset:6144
	ds_read_b64 v[162:163], v222 offset:0
	ds_read_b64 v[164:165], v223 offset:0
	s_waitcnt lgkmcnt(12)
	v_mfma_f32_16x16x32_bf16 v[52:55], v[68:71], v[88:91], v[52:55]
	ds_read_b64 v[178:179], v226 offset:36864
	ds_read_b64 v[180:181], v227 offset:36864
	s_waitcnt lgkmcnt(12)
	v_mfma_f32_16x16x32_bf16 v[60:63], v[68:71], v[92:95], v[60:63]
	ds_read_b64 v[182:183], v226 offset:38912
	ds_read_b64 v[184:185], v227 offset:38912
	s_waitcnt lgkmcnt(12)
	v_mfma_f32_16x16x32_bf16 v[56:59], v[68:71], v[158:161], v[56:59]
	ds_read_b64 v[186:187], v226 offset:40960
	ds_read_b64 v[188:189], v227 offset:40960
	s_waitcnt lgkmcnt(12)
	v_mfma_f32_16x16x32_bf16 v[40:43], v[72:75], v[84:87], v[40:43]
	ds_read_b64 v[190:191], v226 offset:43008
	ds_read_b64 v[192:193], v227 offset:43008
	v_mfma_f32_16x16x32_bf16 v[36:39], v[72:75], v[88:91], v[36:39]
	v_mfma_f32_16x16x32_bf16 v[32:35], v[72:75], v[92:95], v[32:35]
	v_mfma_f32_16x16x32_bf16 v[28:31], v[72:75], v[158:161], v[28:31]
	s_waitcnt lgkmcnt(12)
	v_mfma_f32_16x16x32_bf16 v[24:27], v[76:79], v[84:87], v[24:27]
	ds_read_b64 v[166:167], v222 offset:2048
	ds_read_b64 v[168:169], v223 offset:2048
	v_mfma_f32_16x16x32_bf16 v[20:23], v[76:79], v[88:91], v[20:23]
	v_mfma_f32_16x16x32_bf16 v[16:19], v[76:79], v[92:95], v[16:19]
	v_mfma_f32_16x16x32_bf16 v[12:15], v[76:79], v[158:161], v[12:15]
	s_waitcnt lgkmcnt(12)
	v_mfma_f32_16x16x32_bf16 v[8:11], v[80:83], v[84:87], v[8:11]
	ds_read_b64 v[170:171], v222 offset:4096
	ds_read_b64 v[172:173], v223 offset:4096
	v_mfma_f32_16x16x32_bf16 v[4:7], v[80:83], v[88:91], v[4:7]
	v_mfma_f32_16x16x32_bf16 v[0:3], v[80:83], v[92:95], v[0:3]
	v_mfma_f32_16x16x32_bf16 v[48:51], v[80:83], v[158:161], v[48:51]
	s_waitcnt lgkmcnt(12)
	s_waitcnt lgkmcnt(10)
	v_mfma_f32_16x16x32_bf16 v[44:47], v[162:165], v[178:181], v[44:47]
	ds_read_b64 v[174:175], v222 offset:6144
	ds_read_b64 v[176:177], v223 offset:6144
	s_waitcnt lgkmcnt(10)
	v_mfma_f32_16x16x32_bf16 v[52:55], v[162:165], v[182:185], v[52:55]
	s_waitcnt lgkmcnt(8)
	v_mfma_f32_16x16x32_bf16 v[60:63], v[162:165], v[186:189], v[60:63]
	s_waitcnt lgkmcnt(6)
	v_mfma_f32_16x16x32_bf16 v[56:59], v[162:165], v[190:193], v[56:59]
	s_waitcnt lgkmcnt(4)
	v_mfma_f32_16x16x32_bf16 v[40:43], v[166:169], v[178:181], v[40:43]
	v_mfma_f32_16x16x32_bf16 v[36:39], v[166:169], v[182:185], v[36:39]
	v_mfma_f32_16x16x32_bf16 v[32:35], v[166:169], v[186:189], v[32:35]
	v_mfma_f32_16x16x32_bf16 v[28:31], v[166:169], v[190:193], v[28:31]
	s_waitcnt lgkmcnt(2)
	v_mfma_f32_16x16x32_bf16 v[24:27], v[170:173], v[178:181], v[24:27]
	v_mfma_f32_16x16x32_bf16 v[20:23], v[170:173], v[182:185], v[20:23]
	v_mfma_f32_16x16x32_bf16 v[16:19], v[170:173], v[186:189], v[16:19]
	v_mfma_f32_16x16x32_bf16 v[12:15], v[170:173], v[190:193], v[12:15]
	s_waitcnt lgkmcnt(0)
	v_mfma_f32_16x16x32_bf16 v[8:11], v[174:177], v[178:181], v[8:11]
	v_mfma_f32_16x16x32_bf16 v[4:7], v[174:177], v[182:185], v[4:7]
	v_mfma_f32_16x16x32_bf16 v[0:3], v[174:177], v[186:189], v[0:3]
	v_mfma_f32_16x16x32_bf16 v[48:51], v[174:177], v[190:193], v[48:51]
	s_waitcnt vmcnt(0)
	s_barrier
	s_cmp_eq_u32 s9, 7
	s_cbranch_scc1 .Lg1_skip
	s_add_u32 m0, s7, 0x0
	s_nop 0
	global_load_lds_dwordx4 v64, s[4:5]
	s_add_u32 m0, s7, 0x1000
	s_nop 0
	global_load_lds_dwordx4 v65, s[4:5]
	s_add_u32 m0, s7, 0x2000
	s_nop 0
	global_load_lds_dwordx4 v66, s[4:5]
	s_add_u32 m0, s7, 0x3000
	s_nop 0
	global_load_lds_dwordx4 v67, s[4:5]
	s_add_u32 m0, s7, 0x9000
	s_nop 0
	global_load_lds_dwordx4 v64, s[24:25]
	s_add_u32 m0, s7, 0xa000
	s_nop 0
	global_load_lds_dwordx4 v65, s[24:25]
	s_add_u32 m0, s7, 0xb000
	s_nop 0
	global_load_lds_dwordx4 v66, s[24:25]
	s_add_u32 m0, s7, 0xc000
	s_nop 0
	global_load_lds_dwordx4 v67, s[24:25]
	s_add_u32 s4, s4, 0x80
	s_addc_u32 s5, s5, 0
	s_add_u32 s24, s24, 0x80
	s_addc_u32 s25, s25, 0
.Lg1_skip:
	ds_read_b64 v[68:69], v220 offset:18432
	ds_read_b64 v[70:71], v221 offset:18432
	ds_read_b64 v[84:85], v224 offset:55296
	ds_read_b64 v[86:87], v225 offset:55296
	ds_read_b64 v[88:89], v224 offset:57344
	ds_read_b64 v[90:91], v225 offset:57344
	ds_read_b64 v[92:93], v224 offset:59392
	ds_read_b64 v[94:95], v225 offset:59392
	ds_read_b64 v[158:159], v224 offset:61440
	ds_read_b64 v[160:161], v225 offset:61440
	ds_read_b64 v[72:73], v220 offset:20480
	ds_read_b64 v[74:75], v221 offset:20480
	ds_read_b64 v[76:77], v220 offset:22528
	ds_read_b64 v[78:79], v221 offset:22528
	s_waitcnt lgkmcnt(12)
	s_waitcnt lgkmcnt(10)
	v_mfma_f32_16x16x32_bf16 v[44:47], v[68:71], v[84:87], v[44:47]
	ds_read_b64 v[80:81], v220 offset:24576
	ds_read_b64 v[82:83], v221 offset:24576
	ds_read_b64 v[162:163], v222 offset:18432
	ds_read_b64 v[164:165], v223 offset:18432
	s_waitcnt lgkmcnt(12)
	v_mfma_f32_16x16x32_bf16 v[52:55], v[68:71], v[88:91], v[52:55]
	ds_read_b64 v[178:179], v226 offset:55296
	ds_read_b64 v[180:181], v227 offset:55296
	s_waitcnt lgkmcnt(12)
	v_mfma_f32_16x16x32_bf16 v[60:63], v[68:71], v[92:95], v[60:63]
	ds_read_b64 v[182:183], v226 offset:57344
	ds_read_b64 v[184:185], v227 offset:57344
	s_waitcnt lgkmcnt(12)
	v_mfma_f32_16x16x32_bf16 v[56:59], v[68:71], v[158:161], v[56:59]
	ds_read_b64 v[186:187], v226 offset:59392
	ds_read_b64 v[188:189], v227 offset:59392
	s_waitcnt lgkmcnt(12)
	v_mfma_f32_16x16x32_bf16 v[40:43], v[72:75], v[84:87], v[40:43]
	ds_read_b64 v[190:191], v226 offset:61440
	ds_read_b64 v[192:193], v227 offset:61440
	v_mfma_f32_16x16x32_bf16 v[36:39], v[72:75], v[88:91], v[36:39]
	v_mfma_f32_16x16x32_bf16 v[32:35], v[72:75], v[92:95], v[32:35]
	v_mfma_f32_16x16x32_bf16 v[28:31], v[72:75], v[158:161], v[28:31]
	s_waitcnt lgkmcnt(12)
	v_mfma_f32_16x16x32_bf16 v[24:27], v[76:79], v[84:87], v[24:27]
	ds_read_b64 v[166:167], v222 offset:20480
	ds_read_b64 v[168:169], v223 offset:20480
	v_mfma_f32_16x16x32_bf16 v[20:23], v[76:79], v[88:91], v[20:23]
	v_mfma_f32_16x16x32_bf16 v[16:19], v[76:79], v[92:95], v[16:19]
	v_mfma_f32_16x16x32_bf16 v[12:15], v[76:79], v[158:161], v[12:15]
	s_waitcnt lgkmcnt(12)
	v_mfma_f32_16x16x32_bf16 v[8:11], v[80:83], v[84:87], v[8:11]
	ds_read_b64 v[170:171], v222 offset:22528
	ds_read_b64 v[172:173], v223 offset:22528
	v_mfma_f32_16x16x32_bf16 v[4:7], v[80:83], v[88:91], v[4:7]
	v_mfma_f32_16x16x32_bf16 v[0:3], v[80:83], v[92:95], v[0:3]
	v_mfma_f32_16x16x32_bf16 v[48:51], v[80:83], v[158:161], v[48:51]
	s_waitcnt lgkmcnt(12)
	s_waitcnt lgkmcnt(10)
	v_mfma_f32_16x16x32_bf16 v[44:47], v[162:165], v[178:181], v[44:47]
	ds_read_b64 v[174:175], v222 offset:24576
	ds_read_b64 v[176:177], v223 offset:24576
	s_waitcnt lgkmcnt(10)
	v_mfma_f32_16x16x32_bf16 v[52:55], v[162:165], v[182:185], v[52:55]
	s_waitcnt lgkmcnt(8)
	v_mfma_f32_16x16x32_bf16 v[60:63], v[162:165], v[186:189], v[60:63]
	s_waitcnt lgkmcnt(6)
	v_mfma_f32_16x16x32_bf16 v[56:59], v[162:165], v[190:193], v[56:59]
	s_waitcnt lgkmcnt(4)
	v_mfma_f32_16x16x32_bf16 v[40:43], v[166:169], v[178:181], v[40:43]
	v_mfma_f32_16x16x32_bf16 v[36:39], v[166:169], v[182:185], v[36:39]
	v_mfma_f32_16x16x32_bf16 v[32:35], v[166:169], v[186:189], v[32:35]
	v_mfma_f32_16x16x32_bf16 v[28:31], v[166:169], v[190:193], v[28:31]
	s_waitcnt lgkmcnt(2)
	v_mfma_f32_16x16x32_bf16 v[24:27], v[170:173], v[178:181], v[24:27]
	v_mfma_f32_16x16x32_bf16 v[20:23], v[170:173], v[182:185], v[20:23]
	v_mfma_f32_16x16x32_bf16 v[16:19], v[170:173], v[186:189], v[16:19]
	v_mfma_f32_16x16x32_bf16 v[12:15], v[170:173], v[190:193], v[12:15]
	s_waitcnt lgkmcnt(0)
	v_mfma_f32_16x16x32_bf16 v[8:11], v[174:177], v[178:181], v[8:11]
	v_mfma_f32_16x16x32_bf16 v[4:7], v[174:177], v[182:185], v[4:7]
	v_mfma_f32_16x16x32_bf16 v[0:3], v[174:177], v[186:189], v[0:3]
	v_mfma_f32_16x16x32_bf16 v[48:51], v[174:177], v[190:193], v[48:51]
	s_waitcnt vmcnt(0)
	s_barrier
	s_add_i32 s9, s9, 1
	s_cmp_lg_u32 s9, 8
	s_cbranch_scc1 .Lg1_loop
	s_setprio 0
	s_or_b32 s52, s49, s6
	s_cmp_gt_u32 s8, 31
	s_mov_b64 s[4:5], -1
	s_cbranch_scc0 .LBB0_220
	s_cmp_lt_u32 s8, 48
	s_cbranch_scc1 .LBB0_221
	s_cmp_lt_u32 s8, 56
	s_cbranch_scc1 .LBB0_225
	s_cmp_lt_u32 s8, 64
	s_cbranch_scc1 .LBB0_233
	s_cmpk_lt_u32 s8, 0x48
	s_cbranch_scc1 .LBB0_546
	s_cmpk_lt_u32 s8, 0x50
	s_cbranch_scc1 .LBB0_547
	s_cmpk_lt_u32 s8, 0x70
	s_cbranch_scc1 .LBB0_548
	s_cmpk_lt_u32 s8, 0x90
	s_cbranch_scc1 .LBB0_549
	s_cmpk_lt_u32 s8, 0x98
	s_cbranch_scc1 .LBB0_550
	s_cmpk_lt_u32 s8, 0xa0
	s_mov_b64 s[6:7], 0
	s_cbranch_scc1 .LBB0_551
	s_cmpk_lt_u32 s8, 0xb0
	s_mov_b64 s[30:31], 0
	s_cbranch_scc1 .LBB0_552
	s_cmpk_eq_i32 s52, 0xb00
	s_cbranch_scc1 .LBB0_553
	s_cmpk_lt_u32 s52, 0xd40
	s_cselect_b64 s[8:9], -1, 0
	s_cmpk_gt_u32 s52, 0xd3f
	s_cselect_b64 s[28:29], -1, 0
	s_mov_b64 s[26:27], 0
	s_branch .LBB0_554

.LBB0_912:
	s_or_b64 exec, exec, s[8:9]
	s_lshl_b32 s9, s0, 7
	s_lshl_b32 s0, s21, 7
	v_or_b32_e32 v0, s9, v214
	s_and_b32 s8, s0, 0x380
	s_barrier
	v_readfirstlane_b32 s0, v104
	s_and_b32 s10, s0, 64
	s_lshr_b32 s12, s0, 1
	s_and_b32 s12, s12, 0x7fffffc0
	s_lshr_b32 s0, s0, 6
	s_lshl_b32 s0, s0, 10
	v_bfe_u32 v217, v108, 1, 3
	v_lshlrev_b32_e32 v217, 4, v217
	v_xor_b32_e32 v217, v217, v110
	v_or_b32_e32 v218, s12, v108
	v_lshl_add_u32 v122, v218, 7, v217
	v_xor_b32_e32 v218, 64, v122
	v_or_b32_e32 v219, s10, v108
	v_lshl_add_u32 v109, v219, 7, v217
	v_xor_b32_e32 v219, 64, v109
	v_bfe_u32 v64, v214, 1, 3
	v_and_b32_e32 v65, 7, v104
	v_xor_b32_e32 v64, v64, v65
	v_lshlrev_b32_e32 v64, 4, v64
	v_lshl_add_u32 v64, v214, 11, v64
	v_add_u32_e32 v65, 0x10000, v64
	v_add_u32_e32 v66, 0x20000, v64
	v_add_u32_e32 v67, 0x30000, v64
	v_readlane_b32 s10, v250, 36
	v_readlane_b32 s11, v250, 37
	v_readlane_b32 s22, v249, 4
	v_readlane_b32 s23, v249, 5
	s_lshl_b32 s12, s9, 11
	s_add_u32 s10, s10, s12
	s_addc_u32 s11, s11, 0
	s_lshl_b32 s12, s8, 11
	s_add_u32 s22, s22, s12
	s_addc_u32 s23, s23, 0
	s_add_u32 m0, s0, 0x0
	s_nop 0
	global_load_lds_dwordx4 v64, s[10:11]
	s_add_u32 m0, s0, 0x1000
	s_nop 0
	global_load_lds_dwordx4 v65, s[10:11]
	s_add_u32 m0, s0, 0x2000
	s_nop 0
	global_load_lds_dwordx4 v66, s[10:11]
	s_add_u32 m0, s0, 0x3000
	s_nop 0
	global_load_lds_dwordx4 v67, s[10:11]
	s_add_u32 m0, s0, 0x9000
	s_nop 0
	global_load_lds_dwordx4 v64, s[22:23]
	s_add_u32 m0, s0, 0xa000
	s_nop 0
	global_load_lds_dwordx4 v65, s[22:23]
	s_add_u32 m0, s0, 0xb000
	s_nop 0
	global_load_lds_dwordx4 v66, s[22:23]
	s_add_u32 m0, s0, 0xc000
	s_nop 0
	global_load_lds_dwordx4 v67, s[22:23]
	s_add_u32 s10, s10, 0x80
	s_addc_u32 s11, s11, 0
	s_add_u32 s22, s22, 0x80
	s_addc_u32 s23, s23, 0
	v_mov_b64_e32 v[0:1], 0
	v_mov_b64_e32 v[2:3], 0
	v_mov_b64_e32 v[4:5], 0
	v_mov_b64_e32 v[6:7], 0
	v_mov_b64_e32 v[8:9], 0
	v_mov_b64_e32 v[10:11], 0
	v_mov_b64_e32 v[12:13], 0
	v_mov_b64_e32 v[14:15], 0
	v_mov_b64_e32 v[16:17], 0
	v_mov_b64_e32 v[18:19], 0
	v_mov_b64_e32 v[20:21], 0
	v_mov_b64_e32 v[22:23], 0
	v_mov_b64_e32 v[24:25], 0
	v_mov_b64_e32 v[26:27], 0
	v_mov_b64_e32 v[28:29], 0
	v_mov_b64_e32 v[30:31], 0
	v_mov_b64_e32 v[32:33], 0
	v_mov_b64_e32 v[34:35], 0
	v_mov_b64_e32 v[36:37], 0
	v_mov_b64_e32 v[38:39], 0
	v_mov_b64_e32 v[40:41], 0
	v_mov_b64_e32 v[42:43], 0
	v_mov_b64_e32 v[44:45], 0
	v_mov_b64_e32 v[46:47], 0
	v_mov_b64_e32 v[48:49], 0
	v_mov_b64_e32 v[50:51], 0
	v_mov_b64_e32 v[52:53], 0
	v_mov_b64_e32 v[54:55], 0
	v_mov_b64_e32 v[56:57], 0
	v_mov_b64_e32 v[58:59], 0
	v_mov_b64_e32 v[60:61], 0
	v_mov_b64_e32 v[62:63], 0
	s_mov_b32 s21, 0
	s_waitcnt vmcnt(0)
	s_barrier
	v_bfe_u32 v251, v104, 4, 1
	v_lshlrev_b32_e32 v251, 3, v251
	v_add_u32_e32 v220, v122, v251
	v_sub_u32_e32 v221, v122, v251
	v_add_u32_e32 v221, 8, v221
	v_add_u32_e32 v222, v218, v251
	v_sub_u32_e32 v223, v218, v251
	v_add_u32_e32 v223, 8, v223
	v_add_u32_e32 v224, v109, v251
	v_sub_u32_e32 v225, v109, v251
	v_add_u32_e32 v225, 8, v225
	v_add_u32_e32 v226, v219, v251
	v_sub_u32_e32 v227, v219, v251
	v_add_u32_e32 v227, 8, v227
	s_setprio 2
.Lg4_loop:
	s_add_u32 m0, s0, 0x4800
	s_nop 0
	global_load_lds_dwordx4 v64, s[10:11]
	s_add_u32 m0, s0, 0x5800
	s_nop 0
	global_load_lds_dwordx4 v65, s[10:11]
	s_add_u32 m0, s0, 0x6800
	s_nop 0
	global_load_lds_dwordx4 v66, s[10:11]
	s_add_u32 m0, s0, 0x7800
	s_nop 0
	global_load_lds_dwordx4 v67, s[10:11]
	s_add_u32 m0, s0, 0xd800
	s_nop 0
	global_load_lds_dwordx4 v64, s[22:23]
	s_add_u32 m0, s0, 0xe800
	s_nop 0
	global_load_lds_dwordx4 v65, s[22:23]
	s_add_u32 m0, s0, 0xf800
	s_nop 0
	global_load_lds_dwordx4 v66, s[22:23]
	s_add_u32 m0, s0, 0x10800
	s_nop 0
	global_load_lds_dwordx4 v67, s[22:23]
	s_add_u32 s10, s10, 0x80
	s_addc_u32 s11, s11, 0
	s_add_u32 s22, s22, 0x80
	s_addc_u32 s23, s23, 0
	ds_read_b64 v[68:69], v220 offset:0
	ds_read_b64 v[70:71], v221 offset:0
	ds_read_b64 v[84:85], v224 offset:36864
	ds_read_b64 v[86:87], v225 offset:36864
	ds_read_b64 v[88:89], v224 offset:38912
	ds_read_b64 v[90:91], v225 offset:38912
	ds_read_b64 v[92:93], v224 offset:40960
	ds_read_b64 v[94:95], v225 offset:40960
	ds_read_b64 v[130:131], v224 offset:43008
	ds_read_b64 v[132:133], v225 offset:43008
	ds_read_b64 v[72:73], v220 offset:2048
	ds_read_b64 v[74:75], v221 offset:2048
	ds_read_b64 v[76:77], v220 offset:4096
	ds_read_b64 v[78:79], v221 offset:4096
	s_waitcnt lgkmcnt(12)
	s_waitcnt lgkmcnt(10)
	v_mfma_f32_16x16x32_bf16 v[12:15], v[68:71], v[84:87], v[12:15]
	ds_read_b64 v[80:81], v220 offset:6144
	ds_read_b64 v[82:83], v221 offset:6144
	ds_read_b64 v[134:135], v222 offset:0
	ds_read_b64 v[136:137], v223 offset:0
	s_waitcnt lgkmcnt(12)
	v_mfma_f32_16x16x32_bf16 v[32:35], v[68:71], v[88:91], v[32:35]
	ds_read_b64 v[150:151], v226 offset:36864
	ds_read_b64 v[152:153], v227 offset:36864
	s_waitcnt lgkmcnt(12)
	v_mfma_f32_16x16x32_bf16 v[52:55], v[68:71], v[92:95], v[52:55]
	ds_read_b64 v[154:155], v226 offset:38912
	ds_read_b64 v[156:157], v227 offset:38912
	s_waitcnt lgkmcnt(12)
	v_mfma_f32_16x16x32_bf16 v[56:59], v[68:71], v[130:133], v[56:59]
	ds_read_b64 v[170:171], v226 offset:40960
	ds_read_b64 v[172:173], v227 offset:40960
	s_waitcnt lgkmcnt(12)
	v_mfma_f32_16x16x32_bf16 v[36:39], v[72:75], v[84:87], v[36:39]
	ds_read_b64 v[174:175], v226 offset:43008
	ds_read_b64 v[176:177], v227 offset:43008
	v_mfma_f32_16x16x32_bf16 v[40:43], v[72:75], v[88:91], v[40:43]
	v_mfma_f32_16x16x32_bf16 v[44:47], v[72:75], v[92:95], v[44:47]
	v_mfma_f32_16x16x32_bf16 v[48:51], v[72:75], v[130:133], v[48:51]
	s_waitcnt lgkmcnt(12)
	v_mfma_f32_16x16x32_bf16 v[24:27], v[76:79], v[84:87], v[24:27]
	ds_read_b64 v[138:139], v222 offset:2048
	ds_read_b64 v[140:141], v223 offset:2048
	v_mfma_f32_16x16x32_bf16 v[20:23], v[76:79], v[88:91], v[20:23]
	v_mfma_f32_16x16x32_bf16 v[16:19], v[76:79], v[92:95], v[16:19]
	v_mfma_f32_16x16x32_bf16 v[28:31], v[76:79], v[130:133], v[28:31]
	s_waitcnt lgkmcnt(12)
	v_mfma_f32_16x16x32_bf16 v[0:3], v[80:83], v[84:87], v[0:3]
	ds_read_b64 v[142:143], v222 offset:4096
	ds_read_b64 v[144:145], v223 offset:4096
	v_mfma_f32_16x16x32_bf16 v[4:7], v[80:83], v[88:91], v[4:7]
	v_mfma_f32_16x16x32_bf16 v[8:11], v[80:83], v[92:95], v[8:11]
	v_mfma_f32_16x16x32_bf16 v[60:63], v[80:83], v[130:133], v[60:63]
	s_waitcnt lgkmcnt(12)
	s_waitcnt lgkmcnt(10)
	v_mfma_f32_16x16x32_bf16 v[12:15], v[134:137], v[150:153], v[12:15]
	ds_read_b64 v[146:147], v222 offset:6144
	ds_read_b64 v[148:149], v223 offset:6144
	s_waitcnt lgkmcnt(10)
	v_mfma_f32_16x16x32_bf16 v[32:35], v[134:137], v[154:157], v[32:35]
	s_waitcnt lgkmcnt(8)
	v_mfma_f32_16x16x32_bf16 v[52:55], v[134:137], v[170:173], v[52:55]
	s_waitcnt lgkmcnt(6)
	v_mfma_f32_16x16x32_bf16 v[56:59], v[134:137], v[174:177], v[56:59]
	s_waitcnt lgkmcnt(4)
	v_mfma_f32_16x16x32_bf16 v[36:39], v[138:141], v[150:153], v[36:39]
	v_mfma_f32_16x16x32_bf16 v[40:43], v[138:141], v[154:157], v[40:43]
	v_mfma_f32_16x16x32_bf16 v[44:47], v[138:141], v[170:173], v[44:47]
	v_mfma_f32_16x16x32_bf16 v[48:51], v[138:141], v[174:177], v[48:51]
	s_waitcnt lgkmcnt(2)
	v_mfma_f32_16x16x32_bf16 v[24:27], v[142:145], v[150:153], v[24:27]
	v_mfma_f32_16x16x32_bf16 v[20:23], v[142:145], v[154:157], v[20:23]
	v_mfma_f32_16x16x32_bf16 v[16:19], v[142:145], v[170:173], v[16:19]
	v_mfma_f32_16x16x32_bf16 v[28:31], v[142:145], v[174:177], v[28:31]
	s_waitcnt lgkmcnt(0)
	v_mfma_f32_16x16x32_bf16 v[0:3], v[146:149], v[150:153], v[0:3]
	v_mfma_f32_16x16x32_bf16 v[4:7], v[146:149], v[154:157], v[4:7]
	v_mfma_f32_16x16x32_bf16 v[8:11], v[146:149], v[170:173], v[8:11]
	v_mfma_f32_16x16x32_bf16 v[60:63], v[146:149], v[174:177], v[60:63]
	s_waitcnt vmcnt(0)
	s_barrier
	s_cmp_eq_u32 s21, 7
	s_cbranch_scc1 .Lg4_skip
	s_add_u32 m0, s0, 0x0
	s_nop 0
	global_load_lds_dwordx4 v64, s[10:11]
	s_add_u32 m0, s0, 0x1000
	s_nop 0
	global_load_lds_dwordx4 v65, s[10:11]
	s_add_u32 m0, s0, 0x2000
	s_nop 0
	global_load_lds_dwordx4 v66, s[10:11]
	s_add_u32 m0, s0, 0x3000
	s_nop 0
	global_load_lds_dwordx4 v67, s[10:11]
	s_add_u32 m0, s0, 0x9000
	s_nop 0
	global_load_lds_dwordx4 v64, s[22:23]
	s_add_u32 m0, s0, 0xa000
	s_nop 0
	global_load_lds_dwordx4 v65, s[22:23]
	s_add_u32 m0, s0, 0xb000
	s_nop 0
	global_load_lds_dwordx4 v66, s[22:23]
	s_add_u32 m0, s0, 0xc000
	s_nop 0
	global_load_lds_dwordx4 v67, s[22:23]
	s_add_u32 s10, s10, 0x80
	s_addc_u32 s11, s11, 0
	s_add_u32 s22, s22, 0x80
	s_addc_u32 s23, s23, 0
.Lg4_skip:
	ds_read_b64 v[68:69], v220 offset:18432
	ds_read_b64 v[70:71], v221 offset:18432
	ds_read_b64 v[84:85], v224 offset:55296
	ds_read_b64 v[86:87], v225 offset:55296
	ds_read_b64 v[88:89], v224 offset:57344
	ds_read_b64 v[90:91], v225 offset:57344
	ds_read_b64 v[92:93], v224 offset:59392
	ds_read_b64 v[94:95], v225 offset:59392
	ds_read_b64 v[130:131], v224 offset:61440
	ds_read_b64 v[132:133], v225 offset:61440
	ds_read_b64 v[72:73], v220 offset:20480
	ds_read_b64 v[74:75], v221 offset:20480
	ds_read_b64 v[76:77], v220 offset:22528
	ds_read_b64 v[78:79], v221 offset:22528
	s_waitcnt lgkmcnt(12)
	s_waitcnt lgkmcnt(10)
	v_mfma_f32_16x16x32_bf16 v[12:15], v[68:71], v[84:87], v[12:15]
	ds_read_b64 v[80:81], v220 offset:24576
	ds_read_b64 v[82:83], v221 offset:24576
	ds_read_b64 v[134:135], v222 offset:18432
	ds_read_b64 v[136:137], v223 offset:18432
	s_waitcnt lgkmcnt(12)
	v_mfma_f32_16x16x32_bf16 v[32:35], v[68:71], v[88:91], v[32:35]
	ds_read_b64 v[150:151], v226 offset:55296
	ds_read_b64 v[152:153], v227 offset:55296
	s_waitcnt lgkmcnt(12)
	v_mfma_f32_16x16x32_bf16 v[52:55], v[68:71], v[92:95], v[52:55]
	ds_read_b64 v[154:155], v226 offset:57344
	ds_read_b64 v[156:157], v227 offset:57344
	s_waitcnt lgkmcnt(12)
	v_mfma_f32_16x16x32_bf16 v[56:59], v[68:71], v[130:133], v[56:59]
	ds_read_b64 v[170:171], v226 offset:59392
	ds_read_b64 v[172:173], v227 offset:59392
	s_waitcnt lgkmcnt(12)
	v_mfma_f32_16x16x32_bf16 v[36:39], v[72:75], v[84:87], v[36:39]
	ds_read_b64 v[174:175], v226 offset:61440
	ds_read_b64 v[176:177], v227 offset:61440
	v_mfma_f32_16x16x32_bf16 v[40:43], v[72:75], v[88:91], v[40:43]
	v_mfma_f32_16x16x32_bf16 v[44:47], v[72:75], v[92:95], v[44:47]
	v_mfma_f32_16x16x32_bf16 v[48:51], v[72:75], v[130:133], v[48:51]
	s_waitcnt lgkmcnt(12)
	v_mfma_f32_16x16x32_bf16 v[24:27], v[76:79], v[84:87], v[24:27]
	ds_read_b64 v[138:139], v222 offset:20480
	ds_read_b64 v[140:141], v223 offset:20480
	v_mfma_f32_16x16x32_bf16 v[20:23], v[76:79], v[88:91], v[20:23]
	v_mfma_f32_16x16x32_bf16 v[16:19], v[76:79], v[92:95], v[16:19]
	v_mfma_f32_16x16x32_bf16 v[28:31], v[76:79], v[130:133], v[28:31]
	s_waitcnt lgkmcnt(12)
	v_mfma_f32_16x16x32_bf16 v[0:3], v[80:83], v[84:87], v[0:3]
	ds_read_b64 v[142:143], v222 offset:22528
	ds_read_b64 v[144:145], v223 offset:22528
	v_mfma_f32_16x16x32_bf16 v[4:7], v[80:83], v[88:91], v[4:7]
	v_mfma_f32_16x16x32_bf16 v[8:11], v[80:83], v[92:95], v[8:11]
	v_mfma_f32_16x16x32_bf16 v[60:63], v[80:83], v[130:133], v[60:63]
	s_waitcnt lgkmcnt(12)
	s_waitcnt lgkmcnt(10)
	v_mfma_f32_16x16x32_bf16 v[12:15], v[134:137], v[150:153], v[12:15]
	ds_read_b64 v[146:147], v222 offset:24576
	ds_read_b64 v[148:149], v223 offset:24576
	s_waitcnt lgkmcnt(10)
	v_mfma_f32_16x16x32_bf16 v[32:35], v[134:137], v[154:157], v[32:35]
	s_waitcnt lgkmcnt(8)
	v_mfma_f32_16x16x32_bf16 v[52:55], v[134:137], v[170:173], v[52:55]
	s_waitcnt lgkmcnt(6)
	v_mfma_f32_16x16x32_bf16 v[56:59], v[134:137], v[174:177], v[56:59]
	s_waitcnt lgkmcnt(4)
	v_mfma_f32_16x16x32_bf16 v[36:39], v[138:141], v[150:153], v[36:39]
	v_mfma_f32_16x16x32_bf16 v[40:43], v[138:141], v[154:157], v[40:43]
	v_mfma_f32_16x16x32_bf16 v[44:47], v[138:141], v[170:173], v[44:47]
	v_mfma_f32_16x16x32_bf16 v[48:51], v[138:141], v[174:177], v[48:51]
	s_waitcnt lgkmcnt(2)
	v_mfma_f32_16x16x32_bf16 v[24:27], v[142:145], v[150:153], v[24:27]
	v_mfma_f32_16x16x32_bf16 v[20:23], v[142:145], v[154:157], v[20:23]
	v_mfma_f32_16x16x32_bf16 v[16:19], v[142:145], v[170:173], v[16:19]
	v_mfma_f32_16x16x32_bf16 v[28:31], v[142:145], v[174:177], v[28:31]
	s_waitcnt lgkmcnt(0)
	v_mfma_f32_16x16x32_bf16 v[0:3], v[146:149], v[150:153], v[0:3]
	v_mfma_f32_16x16x32_bf16 v[4:7], v[146:149], v[154:157], v[4:7]
	v_mfma_f32_16x16x32_bf16 v[8:11], v[146:149], v[170:173], v[8:11]
	v_mfma_f32_16x16x32_bf16 v[60:63], v[146:149], v[174:177], v[60:63]
	s_waitcnt vmcnt(0)
	s_barrier
	s_add_i32 s21, s21, 1
	s_cmp_lg_u32 s21, 8
	s_cbranch_scc1 .Lg4_loop
	s_setprio 0
	v_readfirstlane_b32 s0, v104
	s_and_b32 s10, s0, 64
	s_lshr_b32 s0, s0, 1
	s_and_b32 s12, s0, 0x7fffffc0
	s_lshl_b32 s0, s8, 2
	s_add_u32 s8, s36, s0
	s_waitcnt vmcnt(6)
	v_or_b32_e32 v64, s9, v112
	s_addc_u32 s9, s37, 0
	s_lshl_b32 s10, s10, 2
	s_add_u32 s8, s8, s10
	v_add_u32_e32 v116, s12, v64
	s_addc_u32 s9, s9, 0
	v_mov_b32_e32 v115, v117
	v_lshl_add_u64 v[64:65], s[8:9], 0, v[114:115]
	v_lshlrev_b64 v[66:67], 12, v[116:117]
	v_lshl_add_u64 v[68:69], v[64:65], 0, v[66:67]
	v_or_b32_e32 v70, 0x1000, v66
	v_mov_b32_e32 v71, v67
	s_waitcnt vmcnt(5)
	v_lshl_add_u64 v[72:73], v[64:65], 0, v[70:71]
	global_load_dword v106, v[68:69], off
	global_load_dword v107, v[68:69], off offset:64
	global_load_dword v109, v[68:69], off offset:128
	global_load_dword v111, v[68:69], off offset:192
	global_load_dword v113, v[72:73], off
	global_load_dword v116, v[72:73], off offset:64
	global_load_dword v118, v[72:73], off offset:128
	global_load_dword v119, v[72:73], off offset:192
	v_or_b32_e32 v68, 0x2000, v66
	v_mov_b32_e32 v69, v67
	v_lshl_add_u64 v[72:73], v[64:65], 0, v[68:69]
	v_or_b32_e32 v74, 0x3000, v66
	v_mov_b32_e32 v75, v67
	s_waitcnt vmcnt(9)
	v_lshl_add_u64 v[76:77], v[64:65], 0, v[74:75]
	global_load_dword v120, v[72:73], off
	global_load_dword v121, v[72:73], off offset:64
	global_load_dword v122, v[72:73], off offset:128
	global_load_dword v123, v[72:73], off offset:192
	global_load_dword v124, v[76:77], off
	global_load_dword v125, v[76:77], off offset:64
	global_load_dword v126, v[76:77], off offset:128
	global_load_dword v127, v[76:77], off offset:192
	v_or_b32_e32 v72, 0x10000, v66
	v_mov_b32_e32 v73, v67
	v_lshl_add_u64 v[76:77], v[64:65], 0, v[72:73]
	v_or_b32_e32 v78, 0x11000, v66
	v_mov_b32_e32 v79, v67
	v_lshl_add_u64 v[80:81], v[64:65], 0, v[78:79]
	global_load_dword v128, v[76:77], off
	global_load_dword v129, v[76:77], off offset:64
	global_load_dword v130, v[76:77], off offset:128
	global_load_dword v131, v[76:77], off offset:192
	global_load_dword v132, v[80:81], off
	global_load_dword v133, v[80:81], off offset:64
	global_load_dword v134, v[80:81], off offset:128
	global_load_dword v135, v[80:81], off offset:192
	v_or_b32_e32 v76, 0x12000, v66
	v_mov_b32_e32 v77, v67
	v_lshl_add_u64 v[80:81], v[64:65], 0, v[76:77]
	v_or_b32_e32 v82, 0x13000, v66
	v_mov_b32_e32 v83, v67
	v_lshl_add_u64 v[84:85], v[64:65], 0, v[82:83]
	global_load_dword v136, v[80:81], off
	global_load_dword v137, v[80:81], off offset:64
	global_load_dword v138, v[80:81], off offset:128
	global_load_dword v139, v[80:81], off offset:192
	global_load_dword v140, v[84:85], off
	global_load_dword v141, v[84:85], off offset:64
	global_load_dword v142, v[84:85], off offset:128
	global_load_dword v143, v[84:85], off offset:192
	v_or_b32_e32 v80, 0x20000, v66
	v_mov_b32_e32 v81, v67
	v_lshl_add_u64 v[84:85], v[64:65], 0, v[80:81]
	v_or_b32_e32 v86, 0x21000, v66
	v_mov_b32_e32 v87, v67
	v_lshl_add_u64 v[88:89], v[64:65], 0, v[86:87]
	global_load_dword v144, v[84:85], off
	global_load_dword v145, v[84:85], off offset:64
	global_load_dword v146, v[84:85], off offset:128
	global_load_dword v147, v[84:85], off offset:192
	global_load_dword v148, v[88:89], off
	global_load_dword v149, v[88:89], off offset:64
	global_load_dword v150, v[88:89], off offset:128
	global_load_dword v151, v[88:89], off offset:192
	v_or_b32_e32 v84, 0x22000, v66
	v_mov_b32_e32 v85, v67
	v_lshl_add_u64 v[88:89], v[64:65], 0, v[84:85]
	v_or_b32_e32 v90, 0x23000, v66
	v_mov_b32_e32 v91, v67
	s_waitcnt vmcnt(40)
	v_lshl_add_u64 v[92:93], v[64:65], 0, v[90:91]
	global_load_dword v152, v[88:89], off
	global_load_dword v153, v[88:89], off offset:64
	global_load_dword v154, v[88:89], off offset:128
	global_load_dword v155, v[88:89], off offset:192
	global_load_dword v156, v[92:93], off
	global_load_dword v157, v[92:93], off offset:64
	global_load_dword v158, v[92:93], off offset:128
	global_load_dword v159, v[92:93], off offset:192
	v_or_b32_e32 v88, 0x30000, v66
	v_mov_b32_e32 v89, v67
	v_lshl_add_u64 v[92:93], v[64:65], 0, v[88:89]
	v_or_b32_e32 v94, 0x31000, v66
	v_mov_b32_e32 v95, v67
	v_lshl_add_u64 v[100:101], v[64:65], 0, v[94:95]
	global_load_dword v160, v[92:93], off
	global_load_dword v161, v[92:93], off offset:64
	global_load_dword v162, v[92:93], off offset:128
	global_load_dword v163, v[92:93], off offset:192
	global_load_dword v164, v[100:101], off
	global_load_dword v165, v[100:101], off offset:64
	global_load_dword v166, v[100:101], off offset:128
	global_load_dword v167, v[100:101], off offset:192
	v_or_b32_e32 v92, 0x32000, v66
	v_mov_b32_e32 v93, v67
	v_lshl_add_u64 v[100:101], v[64:65], 0, v[92:93]
	v_or_b32_e32 v102, 0x33000, v66
	v_mov_b32_e32 v103, v67
	v_lshl_add_u64 v[64:65], v[64:65], 0, v[102:103]
	global_load_dword v168, v[100:101], off
	global_load_dword v169, v[100:101], off offset:64
	global_load_dword v170, v[100:101], off offset:128
	s_nop 0
	global_load_dword v100, v[100:101], off offset:192
	s_nop 0
	global_load_dword v101, v[64:65], off
	global_load_dword v171, v[64:65], off offset:64
	global_load_dword v172, v[64:65], off offset:128
	global_load_dword v173, v[64:65], off offset:192
	s_add_u32 s0, s52, s0
	s_addc_u32 s9, s53, 0
	s_add_u32 s8, s0, s10
	s_addc_u32 s9, s9, 0
	v_lshl_add_u64 v[64:65], s[8:9], 0, v[114:115]
	v_lshl_add_u64 v[66:67], v[64:65], 0, v[66:67]
	s_waitcnt vmcnt(62)
	v_add_f32_e32 v12, v12, v106
	global_store_dword v[66:67], v12, off
	v_add_f32_e32 v12, v32, v107
	global_store_dword v[66:67], v12, off offset:64
	s_waitcnt vmcnt(62)
	v_add_f32_e32 v12, v52, v109
	global_store_dword v[66:67], v12, off offset:128
	v_add_f32_e32 v12, v56, v111
	global_store_dword v[66:67], v12, off offset:192
	v_lshl_add_u64 v[66:67], v[64:65], 0, v[70:71]
	s_waitcnt vmcnt(62)
	v_add_f32_e32 v12, v13, v113
	global_store_dword v[66:67], v12, off
	v_add_f32_e32 v12, v33, v116
	global_store_dword v[66:67], v12, off offset:64
	s_waitcnt vmcnt(62)
	v_add_f32_e32 v12, v53, v118
	global_store_dword v[66:67], v12, off offset:128
	v_add_f32_e32 v12, v57, v119
	global_store_dword v[66:67], v12, off offset:192
	v_lshl_add_u64 v[12:13], v[64:65], 0, v[68:69]
	s_waitcnt vmcnt(62)
	v_add_f32_e32 v14, v14, v120
	global_store_dword v[12:13], v14, off
	v_add_f32_e32 v14, v34, v121
	global_store_dword v[12:13], v14, off offset:64
	s_waitcnt vmcnt(62)
	v_add_f32_e32 v14, v54, v122
	global_store_dword v[12:13], v14, off offset:128
	v_add_f32_e32 v14, v58, v123
	global_store_dword v[12:13], v14, off offset:192
	v_lshl_add_u64 v[12:13], v[64:65], 0, v[74:75]
	s_waitcnt vmcnt(62)
	v_add_f32_e32 v14, v15, v124
	global_store_dword v[12:13], v14, off
	v_add_f32_e32 v14, v35, v125
	global_store_dword v[12:13], v14, off offset:64
	s_waitcnt vmcnt(62)
	v_add_f32_e32 v14, v55, v126
	global_store_dword v[12:13], v14, off offset:128
	v_add_f32_e32 v14, v59, v127
	global_store_dword v[12:13], v14, off offset:192
	v_lshl_add_u64 v[12:13], v[64:65], 0, v[72:73]
	s_waitcnt vmcnt(62)
	v_add_f32_e32 v14, v36, v128
	global_store_dword v[12:13], v14, off
	v_add_f32_e32 v14, v40, v129
	global_store_dword v[12:13], v14, off offset:64
	s_waitcnt vmcnt(62)
	v_add_f32_e32 v14, v44, v130
	global_store_dword v[12:13], v14, off offset:128
	v_add_f32_e32 v14, v48, v131
	global_store_dword v[12:13], v14, off offset:192
	v_lshl_add_u64 v[12:13], v[64:65], 0, v[78:79]
	s_waitcnt vmcnt(62)
	v_add_f32_e32 v14, v37, v132
	global_store_dword v[12:13], v14, off
	v_add_f32_e32 v14, v41, v133
	global_store_dword v[12:13], v14, off offset:64
	s_waitcnt vmcnt(62)
	v_add_f32_e32 v14, v45, v134
	global_store_dword v[12:13], v14, off offset:128
	v_add_f32_e32 v14, v49, v135
	global_store_dword v[12:13], v14, off offset:192
	v_lshl_add_u64 v[12:13], v[64:65], 0, v[76:77]
	s_waitcnt vmcnt(62)
	v_add_f32_e32 v14, v38, v136
	global_store_dword v[12:13], v14, off
	v_add_f32_e32 v14, v42, v137
	global_store_dword v[12:13], v14, off offset:64
	s_waitcnt vmcnt(62)
	v_add_f32_e32 v14, v46, v138
	global_store_dword v[12:13], v14, off offset:128
	v_add_f32_e32 v14, v50, v139
	global_store_dword v[12:13], v14, off offset:192
	v_lshl_add_u64 v[12:13], v[64:65], 0, v[82:83]
	s_waitcnt vmcnt(62)
	v_add_f32_e32 v14, v39, v140
	global_store_dword v[12:13], v14, off
	v_add_f32_e32 v14, v43, v141
	global_store_dword v[12:13], v14, off offset:64
	s_waitcnt vmcnt(62)
	v_add_f32_e32 v14, v47, v142
	global_store_dword v[12:13], v14, off offset:128
	v_add_f32_e32 v14, v51, v143
	global_store_dword v[12:13], v14, off offset:192
	v_lshl_add_u64 v[12:13], v[64:65], 0, v[80:81]
	s_waitcnt vmcnt(62)
	v_add_f32_e32 v14, v24, v144
	global_store_dword v[12:13], v14, off
	v_add_f32_e32 v14, v20, v145
	global_store_dword v[12:13], v14, off offset:64
	s_waitcnt vmcnt(62)
	v_add_f32_e32 v14, v16, v146
	global_store_dword v[12:13], v14, off offset:128
	v_add_f32_e32 v14, v28, v147
	global_store_dword v[12:13], v14, off offset:192
	v_lshl_add_u64 v[12:13], v[64:65], 0, v[86:87]
	s_waitcnt vmcnt(62)
	v_add_f32_e32 v14, v25, v148
	global_store_dword v[12:13], v14, off
	v_add_f32_e32 v14, v21, v149
	global_store_dword v[12:13], v14, off offset:64
	s_waitcnt vmcnt(62)
	v_add_f32_e32 v14, v17, v150
	global_store_dword v[12:13], v14, off offset:128
	v_add_f32_e32 v14, v29, v151
	global_store_dword v[12:13], v14, off offset:192
	v_lshl_add_u64 v[12:13], v[64:65], 0, v[84:85]
	s_waitcnt vmcnt(62)
	v_add_f32_e32 v14, v26, v152
	global_store_dword v[12:13], v14, off
	v_add_f32_e32 v14, v22, v153
	global_store_dword v[12:13], v14, off offset:64
	s_waitcnt vmcnt(62)
	v_add_f32_e32 v14, v18, v154
	global_store_dword v[12:13], v14, off offset:128
	v_add_f32_e32 v14, v30, v155
	global_store_dword v[12:13], v14, off offset:192
	v_lshl_add_u64 v[12:13], v[64:65], 0, v[90:91]
	s_waitcnt vmcnt(62)
	v_add_f32_e32 v14, v27, v156
	global_store_dword v[12:13], v14, off
	v_add_f32_e32 v14, v23, v157
	global_store_dword v[12:13], v14, off offset:64
	s_waitcnt vmcnt(62)
	v_add_f32_e32 v14, v19, v158
	global_store_dword v[12:13], v14, off offset:128
	v_add_f32_e32 v14, v31, v159
	global_store_dword v[12:13], v14, off offset:192
	v_lshl_add_u64 v[12:13], v[64:65], 0, v[88:89]
	s_waitcnt vmcnt(62)
	v_add_f32_e32 v0, v0, v160
	global_store_dword v[12:13], v0, off
	v_add_f32_e32 v0, v4, v161
	global_store_dword v[12:13], v0, off offset:64
	s_waitcnt vmcnt(62)
	v_add_f32_e32 v0, v8, v162
	global_store_dword v[12:13], v0, off offset:128
	v_add_f32_e32 v0, v60, v163
	global_store_dword v[12:13], v0, off offset:192
	v_lshl_add_u64 v[12:13], v[64:65], 0, v[94:95]
	s_waitcnt vmcnt(62)
	v_add_f32_e32 v0, v1, v164
	global_store_dword v[12:13], v0, off
	v_add_f32_e32 v0, v5, v165
	global_store_dword v[12:13], v0, off offset:64
	s_waitcnt vmcnt(62)
	v_add_f32_e32 v0, v9, v166
	global_store_dword v[12:13], v0, off offset:128
	v_add_f32_e32 v0, v61, v167
	global_store_dword v[12:13], v0, off offset:192
	v_lshl_add_u64 v[0:1], v[64:65], 0, v[92:93]
	s_waitcnt vmcnt(62)
	v_add_f32_e32 v2, v2, v168
	global_store_dword v[0:1], v2, off
	v_add_f32_e32 v2, v6, v169
	global_store_dword v[0:1], v2, off offset:64
	s_waitcnt vmcnt(62)
	v_add_f32_e32 v2, v10, v170
	global_store_dword v[0:1], v2, off offset:128
	v_add_f32_e32 v2, v62, v100
	global_store_dword v[0:1], v2, off offset:192
	v_lshl_add_u64 v[0:1], v[64:65], 0, v[102:103]
	s_waitcnt vmcnt(62)
	v_add_f32_e32 v2, v3, v101
	global_store_dword v[0:1], v2, off
	v_add_f32_e32 v2, v7, v171
	global_store_dword v[0:1], v2, off offset:64
	s_waitcnt vmcnt(62)
	v_add_f32_e32 v2, v11, v172
	global_store_dword v[0:1], v2, off offset:128
	v_add_f32_e32 v2, v63, v173
	global_store_dword v[0:1], v2, off offset:192
	s_branch .LBB0_892
